# PC2 epilogue rewritten as software pipeline: residual loads of row group g+4 issued behind stores of group g
# baseline (speedup 1.0000x reference)
;     __device__ __forceinline__ void operator()(AccT& acc, const Unit& u, int wr, int wc, int fr, int fq) const {
;         const int row0 = u.pm * 256;
;         const char* xb = (const char*)(row0 < TP ? xp + (size_t)row0 * 1024 : xs + (size_t)(row0 - TP) * 1024);
;         char* ob = (char*)(out + (size_t)row0 * 1024);
;         unsigned base = (unsigned)((64 * wr + fr) * 1024 + u.pn * 256 + 64 * wc + 4 * fq) * 4u;
;         asm volatile("" : "+v"(base));
; #pragma unroll
;         for (int ai = 0; ai < 2; ++ai) {
;             f32x4 xv[4][2][2];
; #pragma unroll
;             for (int m = 0; m < 4; ++m)
; #pragma unroll
;                 for (int bj = 0; bj < 2; ++bj)
; #pragma unroll
;                     for (int n = 0; n < 2; ++n) xv[m][bj][n] = *(const f32x4*)(xb + base + (unsigned)((128 * ai + 16 * m) * 1024 + 32 * bj + 16 * n) * 4u);
; #pragma unroll
;             for (int m = 0; m < 4; ++m)
; #pragma unroll
;                 for (int bj = 0; bj < 2; ++bj)
; #pragma unroll
;                     for (int n = 0; n < 2; ++n) *(f32x4*)(ob + base + (unsigned)((128 * ai + 16 * m) * 1024 + 32 * bj + 16 * n) * 4u) = xv[m][bj][n] + acc[ai][bj][m][n];
.LBB0_571:
	v_lshl_add_u32 v140, s53, 10, v155
	s_add_u32 s20, s62, s20
	s_addc_u32 s21, s63, s21
	s_mov_b32 s98, 0x10000
	s_mov_b32 s99, 0
	s_mov_b32 s100, 0x50000
	s_mov_b32 s101, 0
	v_lshl_add_u64 v[230:231], s[22:23], 0, v[140:141]
	v_lshl_add_u64 v[232:233], s[20:21], 0, v[140:141]
	global_load_dwordx4 v[160:163], v[230:231], off
	global_load_dwordx4 v[164:167], v[230:231], off offset:64
	global_load_dwordx4 v[168:171], v[230:231], off offset:128
	global_load_dwordx4 v[172:175], v[230:231], off offset:192
	v_lshl_add_u64 v[230:231], v[230:231], 0, s[98:99]
	global_load_dwordx4 v[176:179], v[230:231], off
	global_load_dwordx4 v[180:183], v[230:231], off offset:64
	global_load_dwordx4 v[184:187], v[230:231], off offset:128
	global_load_dwordx4 v[188:191], v[230:231], off offset:192
	v_lshl_add_u64 v[230:231], v[230:231], 0, s[98:99]
	global_load_dwordx4 v[192:195], v[230:231], off
	global_load_dwordx4 v[196:199], v[230:231], off offset:64
	global_load_dwordx4 v[200:203], v[230:231], off offset:128
	global_load_dwordx4 v[204:207], v[230:231], off offset:192
	v_lshl_add_u64 v[230:231], v[230:231], 0, s[98:99]
	global_load_dwordx4 v[208:211], v[230:231], off
	global_load_dwordx4 v[212:215], v[230:231], off offset:64
	global_load_dwordx4 v[216:219], v[230:231], off offset:128
	global_load_dwordx4 v[220:223], v[230:231], off offset:192
	v_lshl_add_u64 v[230:231], v[230:231], 0, s[100:101]
	s_waitcnt vmcnt(12)
	v_pk_add_f32 v[124:125], v[124:125], v[160:161]
	v_pk_add_f32 v[126:127], v[126:127], v[162:163]
	v_pk_add_f32 v[120:121], v[120:121], v[164:165]
	v_pk_add_f32 v[122:123], v[122:123], v[166:167]
	v_pk_add_f32 v[108:109], v[108:109], v[168:169]
	v_pk_add_f32 v[110:111], v[110:111], v[170:171]
	v_pk_add_f32 v[100:101], v[100:101], v[172:173]
	v_pk_add_f32 v[102:103], v[102:103], v[174:175]
	global_store_dwordx4 v[232:233], v[124:127], off
	global_store_dwordx4 v[232:233], v[120:123], off offset:64
	global_store_dwordx4 v[232:233], v[108:111], off offset:128
	global_store_dwordx4 v[232:233], v[100:103], off offset:192
	v_lshl_add_u64 v[232:233], v[232:233], 0, s[98:99]
	global_load_dwordx4 v[124:127], v[230:231], off
	global_load_dwordx4 v[120:123], v[230:231], off offset:64
	global_load_dwordx4 v[108:111], v[230:231], off offset:128
	global_load_dwordx4 v[100:103], v[230:231], off offset:192
	v_lshl_add_u64 v[230:231], v[230:231], 0, s[98:99]
	s_waitcnt vmcnt(16)
	v_pk_add_f32 v[116:117], v[116:117], v[176:177]
	v_pk_add_f32 v[118:119], v[118:119], v[178:179]
	v_pk_add_f32 v[112:113], v[112:113], v[180:181]
	v_pk_add_f32 v[114:115], v[114:115], v[182:183]
	v_pk_add_f32 v[92:93], v[92:93], v[184:185]
	v_pk_add_f32 v[94:95], v[94:95], v[186:187]
	v_pk_add_f32 v[84:85], v[84:85], v[188:189]
	v_pk_add_f32 v[86:87], v[86:87], v[190:191]
	global_store_dwordx4 v[232:233], v[116:119], off
	global_store_dwordx4 v[232:233], v[112:115], off offset:64
	global_store_dwordx4 v[232:233], v[92:95], off offset:128
	global_store_dwordx4 v[232:233], v[84:87], off offset:192
	v_lshl_add_u64 v[232:233], v[232:233], 0, s[98:99]
	global_load_dwordx4 v[116:119], v[230:231], off
	global_load_dwordx4 v[112:115], v[230:231], off offset:64
	global_load_dwordx4 v[92:95], v[230:231], off offset:128
	global_load_dwordx4 v[84:87], v[230:231], off offset:192
	v_lshl_add_u64 v[230:231], v[230:231], 0, s[98:99]
	s_waitcnt vmcnt(20)
	v_pk_add_f32 v[104:105], v[104:105], v[192:193]
	v_pk_add_f32 v[106:107], v[106:107], v[194:195]
	v_pk_add_f32 v[96:97], v[96:97], v[196:197]
	v_pk_add_f32 v[98:99], v[98:99], v[198:199]
	v_pk_add_f32 v[76:77], v[76:77], v[200:201]
	v_pk_add_f32 v[78:79], v[78:79], v[202:203]
	v_pk_add_f32 v[72:73], v[72:73], v[204:205]
	v_pk_add_f32 v[74:75], v[74:75], v[206:207]
	global_store_dwordx4 v[232:233], v[104:107], off
	global_store_dwordx4 v[232:233], v[96:99], off offset:64
	global_store_dwordx4 v[232:233], v[76:79], off offset:128
	global_store_dwordx4 v[232:233], v[72:75], off offset:192
	v_lshl_add_u64 v[232:233], v[232:233], 0, s[98:99]
	global_load_dwordx4 v[104:107], v[230:231], off
	global_load_dwordx4 v[96:99], v[230:231], off offset:64
	global_load_dwordx4 v[76:79], v[230:231], off offset:128
	global_load_dwordx4 v[72:75], v[230:231], off offset:192
	v_lshl_add_u64 v[230:231], v[230:231], 0, s[98:99]
	s_waitcnt vmcnt(24)
;     __device__ __forceinline__ void operator()(AccT& acc, const Unit& u, int wr, int wc, int fr, int fq) const {
;         const int row0 = u.pm * 256;
;         const char* xb = (const char*)(row0 < TP ? xp + (size_t)row0 * 1024 : xs + (size_t)(row0 - TP) * 1024);
;         char* ob = (char*)(out + (size_t)row0 * 1024);
;         unsigned base = (unsigned)((64 * wr + fr) * 1024 + u.pn * 256 + 64 * wc + 4 * fq) * 4u;
;         asm volatile("" : "+v"(base));
; #pragma unroll
;         for (int ai = 0; ai < 2; ++ai) {
;             f32x4 xv[4][2][2];
; #pragma unroll
;             for (int m = 0; m < 4; ++m)
; #pragma unroll
;                 for (int bj = 0; bj < 2; ++bj)
; #pragma unroll
;                     for (int n = 0; n < 2; ++n) xv[m][bj][n] = *(const f32x4*)(xb + base + (unsigned)((128 * ai + 16 * m) * 1024 + 32 * bj + 16 * n) * 4u);
; #pragma unroll
;             for (int m = 0; m < 4; ++m)
; #pragma unroll
;                 for (int bj = 0; bj < 2; ++bj)
; #pragma unroll
;                     for (int n = 0; n < 2; ++n) *(f32x4*)(ob + base + (unsigned)((128 * ai + 16 * m) * 1024 + 32 * bj + 16 * n) * 4u) = xv[m][bj][n] + acc[ai][bj][m][n];
;             asm volatile("" ::: "memory");
;         }
	v_pk_add_f32 v[88:89], v[88:89], v[208:209]
	v_pk_add_f32 v[90:91], v[90:91], v[210:211]
	v_pk_add_f32 v[80:81], v[80:81], v[212:213]
	v_pk_add_f32 v[82:83], v[82:83], v[214:215]
	v_pk_add_f32 v[68:69], v[68:69], v[216:217]
	v_pk_add_f32 v[70:71], v[70:71], v[218:219]
	v_pk_add_f32 v[64:65], v[64:65], v[220:221]
	v_pk_add_f32 v[66:67], v[66:67], v[222:223]
	global_store_dwordx4 v[232:233], v[88:91], off
	global_store_dwordx4 v[232:233], v[80:83], off offset:64
	global_store_dwordx4 v[232:233], v[68:71], off offset:128
	global_store_dwordx4 v[232:233], v[64:67], off offset:192
	v_lshl_add_u64 v[232:233], v[232:233], 0, s[100:101]
	global_load_dwordx4 v[88:91], v[230:231], off
	global_load_dwordx4 v[80:83], v[230:231], off offset:64
	global_load_dwordx4 v[68:71], v[230:231], off offset:128
	global_load_dwordx4 v[64:67], v[230:231], off offset:192
	s_waitcnt vmcnt(24)
	v_pk_add_f32 v[60:61], v[60:61], v[124:125]
	v_pk_add_f32 v[62:63], v[62:63], v[126:127]
	v_pk_add_f32 v[56:57], v[56:57], v[120:121]
	v_pk_add_f32 v[58:59], v[58:59], v[122:123]
	v_pk_add_f32 v[40:41], v[40:41], v[108:109]
	v_pk_add_f32 v[42:43], v[42:43], v[110:111]
	v_pk_add_f32 v[36:37], v[36:37], v[100:101]
	v_pk_add_f32 v[38:39], v[38:39], v[102:103]
	global_store_dwordx4 v[232:233], v[60:63], off
	global_store_dwordx4 v[232:233], v[56:59], off offset:64
	global_store_dwordx4 v[232:233], v[40:43], off offset:128
	global_store_dwordx4 v[232:233], v[36:39], off offset:192
	v_lshl_add_u64 v[232:233], v[232:233], 0, s[98:99]
	s_waitcnt vmcnt(20)
	v_pk_add_f32 v[52:53], v[52:53], v[116:117]
	v_pk_add_f32 v[54:55], v[54:55], v[118:119]
	v_pk_add_f32 v[48:49], v[48:49], v[112:113]
	v_pk_add_f32 v[50:51], v[50:51], v[114:115]
	v_pk_add_f32 v[28:29], v[28:29], v[92:93]
	v_pk_add_f32 v[30:31], v[30:31], v[94:95]
	v_pk_add_f32 v[24:25], v[24:25], v[84:85]
	v_pk_add_f32 v[26:27], v[26:27], v[86:87]
	global_store_dwordx4 v[232:233], v[52:55], off
	global_store_dwordx4 v[232:233], v[48:51], off offset:64
	global_store_dwordx4 v[232:233], v[28:31], off offset:128
	global_store_dwordx4 v[232:233], v[24:27], off offset:192
	v_lshl_add_u64 v[232:233], v[232:233], 0, s[98:99]
	s_waitcnt vmcnt(16)
	v_pk_add_f32 v[44:45], v[44:45], v[104:105]
	v_pk_add_f32 v[46:47], v[46:47], v[106:107]
	v_pk_add_f32 v[32:33], v[32:33], v[96:97]
	v_pk_add_f32 v[34:35], v[34:35], v[98:99]
	v_pk_add_f32 v[16:17], v[16:17], v[76:77]
	v_pk_add_f32 v[18:19], v[18:19], v[78:79]
	v_pk_add_f32 v[12:13], v[12:13], v[72:73]
	v_pk_add_f32 v[14:15], v[14:15], v[74:75]
	global_store_dwordx4 v[232:233], v[44:47], off
	global_store_dwordx4 v[232:233], v[32:35], off offset:64
	global_store_dwordx4 v[232:233], v[16:19], off offset:128
	global_store_dwordx4 v[232:233], v[12:15], off offset:192
	v_lshl_add_u64 v[232:233], v[232:233], 0, s[98:99]
	s_waitcnt vmcnt(12)
	v_pk_add_f32 v[20:21], v[20:21], v[88:89]
	v_pk_add_f32 v[22:23], v[22:23], v[90:91]
	v_pk_add_f32 v[8:9], v[8:9], v[80:81]
	v_pk_add_f32 v[10:11], v[10:11], v[82:83]
	v_pk_add_f32 v[4:5], v[4:5], v[68:69]
	v_pk_add_f32 v[6:7], v[6:7], v[70:71]
	v_pk_add_f32 v[0:1], v[0:1], v[64:65]
	v_pk_add_f32 v[2:3], v[2:3], v[66:67]
	global_store_dwordx4 v[232:233], v[20:23], off
	global_store_dwordx4 v[232:233], v[8:11], off offset:64
	global_store_dwordx4 v[232:233], v[4:7], off offset:128
	global_store_dwordx4 v[232:233], v[0:3], off offset:192
	s_andn2_b64 vcc, exec, s[0:1]
	s_mov_b64 s[0:1], -1
	s_cbranch_vccnz .LBB0_560
	s_andn2_b64 vcc, exec, s[6:7]
	s_cbranch_vccnz .LBB0_559
	s_barrier
	s_branch .LBB0_559

; __global__ void __launch_bounds__(512, 2) fwd_kernel(Args a) {
	.amdhsa_kernel _Z10fwd_kernel4Args
		.amdhsa_group_segment_fixed_size 0
		.amdhsa_private_segment_fixed_size 0
		.amdhsa_kernarg_size 384
		.amdhsa_user_sgpr_count 2
		.amdhsa_user_sgpr_dispatch_ptr 0
		.amdhsa_user_sgpr_queue_ptr 0
		.amdhsa_user_sgpr_kernarg_segment_ptr 1
		.amdhsa_user_sgpr_dispatch_id 0
		.amdhsa_user_sgpr_kernarg_preload_length 0
		.amdhsa_user_sgpr_kernarg_preload_offset 0
		.amdhsa_user_sgpr_private_segment_size 0
		.amdhsa_uses_dynamic_stack 0
		.amdhsa_enable_private_segment 0
		.amdhsa_system_sgpr_workgroup_id_x 1
		.amdhsa_system_sgpr_workgroup_id_y 0
		.amdhsa_system_sgpr_workgroup_id_z 0
		.amdhsa_system_sgpr_workgroup_info 0
		.amdhsa_system_vgpr_workitem_id 2
		.amdhsa_next_free_vgpr 250
		.amdhsa_next_free_sgpr 102
		.amdhsa_accum_offset 252
		.amdhsa_reserve_vcc 1
		.amdhsa_float_round_mode_32 0
		.amdhsa_float_round_mode_16_64 0
		.amdhsa_float_denorm_mode_32 3
		.amdhsa_float_denorm_mode_16_64 3
		.amdhsa_dx10_clamp 1
		.amdhsa_ieee_mode 1
		.amdhsa_fp16_overflow 0
		.amdhsa_tg_split 0
		.amdhsa_exception_fp_ieee_invalid_op 0
		.amdhsa_exception_fp_denorm_src 0
		.amdhsa_exception_fp_ieee_div_zero 0
		.amdhsa_exception_fp_ieee_overflow 0
		.amdhsa_exception_fp_ieee_underflow 0
		.amdhsa_exception_fp_ieee_inexact 0
		.amdhsa_exception_int_div_zero 0
	.end_amdhsa_kernel

; __global__ void __launch_bounds__(512, 2) fwd_kernel(Args a) {
amdhsa.kernels:
  - .agpr_count:     0
    .args:
      - .offset:         0
        .size:           128
        .value_kind:     by_value
      - .offset:         128
        .size:           4
        .value_kind:     hidden_block_count_x
      - .offset:         132
        .size:           4
        .value_kind:     hidden_block_count_y
      - .offset:         136
        .size:           4
        .value_kind:     hidden_block_count_z
      - .offset:         140
        .size:           2
        .value_kind:     hidden_group_size_x
      - .offset:         142
        .size:           2
        .value_kind:     hidden_group_size_y
      - .offset:         144
        .size:           2
        .value_kind:     hidden_group_size_z
      - .offset:         146
        .size:           2
        .value_kind:     hidden_remainder_x
      - .offset:         148
        .size:           2
        .value_kind:     hidden_remainder_y
      - .offset:         150
        .size:           2
        .value_kind:     hidden_remainder_z
      - .offset:         168
        .size:           8
        .value_kind:     hidden_global_offset_x
      - .offset:         176
        .size:           8
        .value_kind:     hidden_global_offset_y
      - .offset:         184
        .size:           8
        .value_kind:     hidden_global_offset_z
      - .offset:         192
        .size:           2
        .value_kind:     hidden_grid_dims
      - .offset:         216
        .size:           8
        .value_kind:     hidden_multigrid_sync_arg
      - .offset:         248
        .size:           4
        .value_kind:     hidden_dynamic_lds_size
    .group_segment_fixed_size: 0
    .kernarg_segment_align: 8
    .kernarg_segment_size: 384
    .language:       OpenCL C
    .language_version:
      - 2
      - 0
    .max_flat_workgroup_size: 512
    .name:           _Z10fwd_kernel4Args
    .private_segment_fixed_size: 0
    .sgpr_count:     108
    .sgpr_spill_count: 102
    .symbol:         _Z10fwd_kernel4Args.kd
    .uniform_work_group_size: 1
    .uses_dynamic_stack: false
    .vgpr_count:     250
    .vgpr_spill_count: 0
    .wavefront_size: 64
